# mixer phase: workgroups with blockIdx bit 5 set run their pool unit before their RNN unit, so memory-bound pool units overlap latency-bound RNN units of other workgroups
# speedup vs baseline: 1.0076x; 1.0076x over previous
.LBB0_81:
	s_andn2_b64 vcc, exec, s[0:1]
	s_cbranch_vccnz .LBB0_147
	v_readlane_b32 s0, v253, 37
	v_readlane_b32 s1, v253, 38
	s_andn2_b64 vcc, exec, s[0:1]
	s_cbranch_vccnz .LBB0_147
	s_mov_b32 s100, s62
	s_mov_b32 s101, s64
	s_ashr_i32 s65, s64, 31
	s_lshl_b32 s15, s64, 5
	s_lshl_b32 s2, s64, 10
	s_lshl_b64 s[10:11], s[64:65], 12
	s_lshl_b64 s[0:1], s[64:65], 14
	s_mov_b32 s6, s62
	v_readlane_b32 s52, v253, 15
	v_readlane_b32 s58, v253, 21
	v_readlane_b32 s59, v253, 22
	v_readlane_b32 s66, v253, 29
	s_mov_b64 s[58:59], s[10:11]
	v_readlane_b32 s67, v253, 30
	s_add_u32 s34, s66, s58
	v_readlane_b32 s56, v253, 19
	v_readlane_b32 s57, v253, 20
	v_readlane_b32 s64, v253, 27
	s_addc_u32 s35, s67, s59
	v_readlane_b32 s53, v253, 16
	v_readlane_b32 s54, v253, 17
	v_readlane_b32 s55, v253, 18
	v_readlane_b32 s65, v253, 28
	s_add_u32 s18, s64, s0
	v_readlane_b32 s56, v255, 27
	s_mov_b32 s55, s6
	s_addc_u32 s19, s65, s1
	v_readlane_b32 s22, v253, 0
	v_readlane_b32 s52, v255, 22
	v_readlane_b32 s53, v255, 23
	v_readlane_b32 s54, v255, 24
	v_readlane_b32 s57, v255, 28
	v_readlane_b32 s60, v253, 23
	v_readlane_b32 s61, v253, 24
	v_readlane_b32 s62, v253, 25
	v_readlane_b32 s63, v253, 26
	v_readlane_b32 s23, v253, 0
	s_bitcmp1_b32 s23, 5
	s_cbranch_scc1 .LBB0_117
	s_branch .LBB0_85

.Lmix_pool_done:
	v_readlane_b32 s20, v253, 0
	s_bitcmp1_b32 s20, 5
	s_cbranch_scc0 .LBB0_146
	s_mov_b32 s62, s100
	s_mov_b32 s64, s101
	s_ashr_i32 s65, s64, 31
	s_lshl_b32 s15, s64, 5
	s_lshl_b32 s2, s64, 10
	s_lshl_b64 s[10:11], s[64:65], 12
	s_lshl_b64 s[0:1], s[64:65], 14
	s_mov_b32 s6, s62
	v_readlane_b32 s52, v253, 15
	v_readlane_b32 s58, v253, 21
	v_readlane_b32 s59, v253, 22
	v_readlane_b32 s66, v253, 29
	s_mov_b64 s[58:59], s[10:11]
	v_readlane_b32 s67, v253, 30
	s_add_u32 s34, s66, s58
	v_readlane_b32 s56, v253, 19
	v_readlane_b32 s57, v253, 20
	v_readlane_b32 s64, v253, 27
	s_addc_u32 s35, s67, s59
	v_readlane_b32 s53, v253, 16
	v_readlane_b32 s54, v253, 17
	v_readlane_b32 s55, v253, 18
	v_readlane_b32 s65, v253, 28
	s_add_u32 s18, s64, s0
	v_readlane_b32 s56, v255, 27
	s_mov_b32 s55, s6
	s_addc_u32 s19, s65, s1
	v_readlane_b32 s22, v253, 0
	v_readlane_b32 s52, v255, 22
	v_readlane_b32 s53, v255, 23
	v_readlane_b32 s54, v255, 24
	v_readlane_b32 s57, v255, 28
	v_readlane_b32 s60, v253, 23
	v_readlane_b32 s61, v253, 24
	v_readlane_b32 s62, v253, 25
	v_readlane_b32 s63, v253, 26
	s_branch .LBB0_85
.Lmix_rnn_done:
	v_readlane_b32 s23, v253, 0
	s_bitcmp1_b32 s23, 5
	s_cbranch_scc0 .LBB0_117
	v_readlane_b32 s22, v255, 32
	v_readlane_b32 s23, v255, 33
	s_movk_i32 s61, 0xfff
	s_branch .LBB0_146
